# G2 merge loop: 6 loads in flight per thread; prep CNP loop: next-iteration loads prefetched into shadow registers
# baseline (speedup 1.0000x reference)
.LBB0_137:
	s_lshl_b32 s20, s16, 2
	s_lshl_b32 s18, s3, 5
	s_cmpk_gt_i32 s16, 0x7fff
	s_cbranch_scc1 .LBB0_140
	v_and_b32_e32 v2, 64, v210
	v_add_u32_e32 v2, 64, v2
	v_xor_b32_e32 v4, 1, v210
	v_cmp_lt_i32_e32 vcc, v4, v2
	s_ashr_i32 s21, s20, 31
	s_lshl_b64 s[8:9], s[20:21], 10
	v_cndmask_b32_e32 v4, v210, v4, vcc
	v_lshlrev_b32_e32 v40, 2, v4
	v_xor_b32_e32 v4, 2, v210
	v_cmp_lt_i32_e32 vcc, v4, v2
	s_add_u32 s8, s0, s8
	s_load_dwordx2 s[6:7], s[14:15], 0x18
	v_cndmask_b32_e32 v4, v210, v4, vcc
	v_lshlrev_b32_e32 v41, 2, v4
	v_xor_b32_e32 v4, 4, v210
	v_cmp_lt_i32_e32 vcc, v4, v2
	v_mov_b32_e32 v37, v3
	s_addc_u32 s9, s1, s9
	v_cndmask_b32_e32 v4, v210, v4, vcc
	v_lshlrev_b32_e32 v42, 2, v4
	v_xor_b32_e32 v4, 8, v210
	v_cmp_lt_i32_e32 vcc, v4, v2
	s_ashr_i32 s19, s18, 31
	s_mov_b32 s61, s79
	v_cndmask_b32_e32 v4, v210, v4, vcc
	v_lshlrev_b32_e32 v43, 2, v4
	v_xor_b32_e32 v4, 16, v210
	v_cmp_lt_i32_e32 vcc, v4, v2
	s_lshl_b64 s[16:17], s[18:19], 10
	s_lshl_b64 s[10:11], s[20:21], 11
	v_cndmask_b32_e32 v4, v210, v4, vcc
	v_lshlrev_b32_e32 v44, 2, v4
	v_xor_b32_e32 v4, 32, v210
	v_cmp_lt_i32_e32 vcc, v4, v2
	s_nop 1
	v_cndmask_b32_e32 v2, v210, v4, vcc
	v_lshl_add_u64 v[4:5], s[8:9], 0, v[36:37]
	s_mov_b64 s[8:9], 0x6500000
	v_lshl_add_u64 v[36:37], v[4:5], 0, s[8:9]
	s_lshl_b64 s[8:9], s[60:61], 28
	s_add_u32 s5, s8, s10
	s_addc_u32 s8, s9, s11
	s_waitcnt lgkmcnt(0)
	s_add_u32 s6, s6, s5
	v_lshlrev_b32_e32 v45, 2, v2
	v_lshlrev_b32_e32 v2, 4, v82
	s_addc_u32 s7, s7, s8
	v_lshl_add_u64 v[4:5], s[6:7], 0, v[2:3]
	s_mov_b64 s[6:7], 0x1000
	v_lshl_add_u64 v[38:39], v[4:5], 0, s[6:7]
	s_lshl_b64 s[22:23], s[18:19], 11
	s_mov_b32 s5, s20
	global_load_dwordx4 v[128:131], v[38:39], off offset:-4096
	global_load_dwordx4 v[124:127], v[38:39], off offset:-3072
	global_load_dwordx4 v[120:123], v[38:39], off offset:-2048
	global_load_dwordx4 v[116:119], v[38:39], off offset:-1024
	global_load_dwordx4 v[112:115], v[38:39], off
	global_load_dwordx4 v[108:111], v[38:39], off offset:1024
	global_load_dwordx4 v[104:107], v[38:39], off offset:2048
	global_load_dwordx4 v[100:103], v[38:39], off offset:3072
	s_waitcnt vmcnt(0)
	s_branch .Lcnp_body
.LBB0_139:
	s_waitcnt vmcnt(8)
.Lcnp_body:
	v_mov_b32_e32 v4, v100
	v_mov_b32_e32 v5, v101
	v_mov_b32_e32 v6, v102
	v_mov_b32_e32 v7, v103
	v_mov_b32_e32 v8, v104
	v_mov_b32_e32 v9, v105
	v_mov_b32_e32 v10, v106
	v_mov_b32_e32 v11, v107
	v_mov_b32_e32 v12, v108
	v_mov_b32_e32 v13, v109
	v_mov_b32_e32 v14, v110
	v_mov_b32_e32 v15, v111
	v_mov_b32_e32 v16, v112
	v_mov_b32_e32 v17, v113
	v_mov_b32_e32 v18, v114
	v_mov_b32_e32 v19, v115
	v_mov_b32_e32 v20, v116
	v_mov_b32_e32 v21, v117
	v_mov_b32_e32 v22, v118
	v_mov_b32_e32 v23, v119
	v_mov_b32_e32 v24, v120
	v_mov_b32_e32 v25, v121
	v_mov_b32_e32 v26, v122
	v_mov_b32_e32 v27, v123
	v_mov_b32_e32 v28, v124
	v_mov_b32_e32 v29, v125
	v_mov_b32_e32 v30, v126
	v_mov_b32_e32 v31, v127
	v_mov_b32_e32 v32, v128
	v_mov_b32_e32 v33, v129
	v_mov_b32_e32 v34, v130
	v_mov_b32_e32 v35, v131
	s_add_i32 s5, s5, s18
	v_lshl_add_u64 v[38:39], v[38:39], 0, s[22:23]
	s_cmp_gt_i32 s5, 0x1ffff
	s_cbranch_scc1 .Lcnp_nopf
	global_load_dwordx4 v[128:131], v[38:39], off offset:-4096
	global_load_dwordx4 v[124:127], v[38:39], off offset:-3072
	global_load_dwordx4 v[120:123], v[38:39], off offset:-2048
	global_load_dwordx4 v[116:119], v[38:39], off offset:-1024
	global_load_dwordx4 v[112:115], v[38:39], off
	global_load_dwordx4 v[108:111], v[38:39], off offset:1024
	global_load_dwordx4 v[104:107], v[38:39], off offset:2048
	global_load_dwordx4 v[100:103], v[38:39], off offset:3072
.Lcnp_nopf:
	v_mov_b32_e32 v48, v33
	v_mov_b32_e32 v49, v29
	v_mov_b32_e32 v52, v35
	v_mov_b32_e32 v53, v31
	v_mov_b32_e32 v46, v32
	v_mov_b32_e32 v47, v28
	v_mov_b32_e32 v50, v34
	v_mov_b32_e32 v51, v30
	v_mov_b32_e32 v56, v25
	v_mov_b32_e32 v57, v21
	v_mov_b32_e32 v60, v27
	v_mov_b32_e32 v61, v23
	v_pk_mul_f32 v[48:49], v[48:49], v[48:49]
	v_pk_mul_f32 v[52:53], v[52:53], v[52:53]
	v_mov_b32_e32 v54, v24
	v_mov_b32_e32 v55, v20
	v_mov_b32_e32 v58, v26
	v_mov_b32_e32 v59, v22
	v_mov_b32_e32 v64, v17
	v_mov_b32_e32 v65, v13
	v_mov_b32_e32 v70, v19
	v_mov_b32_e32 v71, v15
	v_pk_mul_f32 v[56:57], v[56:57], v[56:57]
	v_pk_mul_f32 v[60:61], v[60:61], v[60:61]
	v_pk_fma_f32 v[46:47], v[46:47], v[46:47], v[48:49]
	v_pk_fma_f32 v[48:49], v[50:51], v[50:51], v[52:53]
	v_mov_b32_e32 v62, v16
	v_mov_b32_e32 v63, v12
	v_mov_b32_e32 v66, v18
	v_mov_b32_e32 v67, v14
	v_mov_b32_e32 v74, v9
	v_mov_b32_e32 v75, v5
	v_mov_b32_e32 v78, v11
	v_mov_b32_e32 v79, v7
	v_pk_mul_f32 v[64:65], v[64:65], v[64:65]
	v_pk_mul_f32 v[70:71], v[70:71], v[70:71]
	v_pk_fma_f32 v[50:51], v[54:55], v[54:55], v[56:57]
	v_pk_fma_f32 v[52:53], v[58:59], v[58:59], v[60:61]
	v_pk_add_f32 v[46:47], v[46:47], v[48:49]
	v_mov_b32_e32 v72, v8
	v_mov_b32_e32 v73, v4
	v_mov_b32_e32 v76, v10
	v_mov_b32_e32 v77, v6
	v_pk_mul_f32 v[74:75], v[74:75], v[74:75]
	v_pk_mul_f32 v[78:79], v[78:79], v[78:79]
	v_pk_fma_f32 v[54:55], v[62:63], v[62:63], v[64:65]
	v_pk_fma_f32 v[56:57], v[66:67], v[66:67], v[70:71]
	v_pk_add_f32 v[48:49], v[50:51], v[52:53]
	v_add_f32_e32 v2, v46, v47
	v_pk_fma_f32 v[58:59], v[72:73], v[72:73], v[74:75]
	v_pk_fma_f32 v[60:61], v[76:77], v[76:77], v[78:79]
	v_pk_add_f32 v[50:51], v[54:55], v[56:57]
	v_add_f32_e32 v46, v48, v49
	ds_bpermute_b32 v49, v40, v2
	v_pk_add_f32 v[52:53], v[58:59], v[60:61]
	v_add_f32_e32 v47, v50, v51
	ds_bpermute_b32 v50, v40, v46
	v_add_f32_e32 v48, v52, v53
	ds_bpermute_b32 v51, v40, v47
	ds_bpermute_b32 v52, v40, v48
	s_waitcnt lgkmcnt(3)
	v_add_f32_e32 v2, v2, v49
	s_waitcnt lgkmcnt(2)
	v_add_f32_e32 v46, v46, v50
	ds_bpermute_b32 v49, v41, v2
	s_waitcnt lgkmcnt(2)
	v_add_f32_e32 v47, v47, v51
	ds_bpermute_b32 v50, v41, v46
	s_waitcnt lgkmcnt(2)
	v_add_f32_e32 v48, v48, v52
	ds_bpermute_b32 v51, v41, v47
	ds_bpermute_b32 v52, v41, v48
	s_waitcnt lgkmcnt(3)
	v_add_f32_e32 v2, v2, v49
	s_waitcnt lgkmcnt(2)
	v_add_f32_e32 v46, v46, v50
	ds_bpermute_b32 v49, v42, v2
	s_waitcnt lgkmcnt(2)
	v_add_f32_e32 v47, v47, v51
	ds_bpermute_b32 v50, v42, v46
	s_waitcnt lgkmcnt(2)
	v_add_f32_e32 v48, v48, v52
	ds_bpermute_b32 v51, v42, v47
	ds_bpermute_b32 v52, v42, v48
	s_waitcnt lgkmcnt(3)
	v_add_f32_e32 v2, v2, v49
	s_waitcnt lgkmcnt(2)
	v_add_f32_e32 v46, v46, v50
	ds_bpermute_b32 v49, v43, v2
	s_waitcnt lgkmcnt(2)
	v_add_f32_e32 v47, v47, v51
	ds_bpermute_b32 v50, v43, v46
	s_waitcnt lgkmcnt(2)
	v_add_f32_e32 v48, v48, v52
	ds_bpermute_b32 v51, v43, v47
	ds_bpermute_b32 v52, v43, v48
	s_waitcnt lgkmcnt(3)
	v_add_f32_e32 v2, v2, v49
	s_waitcnt lgkmcnt(2)
	v_add_f32_e32 v46, v46, v50
	ds_bpermute_b32 v49, v44, v2
	s_waitcnt lgkmcnt(2)
	v_add_f32_e32 v47, v47, v51
	ds_bpermute_b32 v50, v44, v46
	s_waitcnt lgkmcnt(2)
	v_add_f32_e32 v48, v48, v52
	ds_bpermute_b32 v51, v44, v47
	ds_bpermute_b32 v52, v44, v48
	s_waitcnt lgkmcnt(3)
	v_add_f32_e32 v2, v2, v49
	s_waitcnt lgkmcnt(2)
	v_add_f32_e32 v46, v46, v50
	ds_bpermute_b32 v49, v45, v2
	s_waitcnt lgkmcnt(2)
	v_add_f32_e32 v47, v47, v51
	ds_bpermute_b32 v50, v45, v46
	s_waitcnt lgkmcnt(2)
	v_add_f32_e32 v48, v48, v52
	ds_bpermute_b32 v51, v45, v47
	ds_bpermute_b32 v52, v45, v48
	s_waitcnt lgkmcnt(3)
	v_add_f32_e32 v2, v2, v49
	s_waitcnt lgkmcnt(2)
	v_add_f32_e32 v46, v46, v50
	v_fmamk_f32 v2, v2, 0x3b000000, v201
	s_waitcnt lgkmcnt(1)
	v_add_f32_e32 v47, v47, v51
	v_fmamk_f32 v46, v46, 0x3b000000, v201
	v_mul_f32_e32 v49, 0x4f800000, v2
	v_cmp_gt_f32_e64 s[46:47], s91, v2
	s_waitcnt lgkmcnt(0)
	v_add_f32_e32 v48, v48, v52
	v_fmamk_f32 v47, v47, 0x3b000000, v201
	v_mul_f32_e32 v50, 0x4f800000, v46
	v_cmp_gt_f32_e32 vcc, s91, v46
	v_cndmask_b32_e64 v2, v2, v49, s[46:47]
	v_fmamk_f32 v48, v48, 0x3b000000, v201
	v_mul_f32_e32 v51, 0x4f800000, v47
	v_cmp_gt_f32_e64 s[42:43], s91, v47
	v_cndmask_b32_e32 v46, v46, v50, vcc
	v_sqrt_f32_e32 v49, v2
	v_mul_f32_e32 v52, 0x4f800000, v48
	v_cmp_gt_f32_e64 s[44:45], s91, v48
	v_cndmask_b32_e64 v47, v47, v51, s[42:43]
	v_sqrt_f32_e32 v50, v46
	v_cndmask_b32_e64 v48, v48, v52, s[44:45]
	v_sqrt_f32_e32 v51, v47
	v_sqrt_f32_e32 v52, v48
	v_add_u32_e32 v53, -1, v49
	v_add_u32_e32 v54, 1, v49
	v_add_u32_e32 v55, -1, v50
	v_fma_f32 v61, -v53, v49, v2
	v_add_u32_e32 v56, 1, v50
	v_add_u32_e32 v57, -1, v51
	v_fma_f32 v62, -v54, v49, v2
	v_fma_f32 v63, -v55, v50, v46
	v_cmp_ge_f32_e64 s[48:49], 0, v61
	v_add_u32_e32 v58, 1, v51
	v_add_u32_e32 v59, -1, v52
	v_fma_f32 v64, -v56, v50, v46
	v_fma_f32 v65, -v57, v51, v47
	v_cndmask_b32_e64 v49, v49, v53, s[48:49]
	v_cmp_ge_f32_e64 s[48:49], 0, v63
	v_cmp_lt_f32_e64 s[54:55], 0, v62
	v_add_u32_e32 v60, 1, v52
	v_fma_f32 v66, -v58, v51, v47
	v_fma_f32 v67, -v59, v52, v48
	v_cndmask_b32_e64 v50, v50, v55, s[48:49]
	v_cmp_lt_f32_e64 s[48:49], 0, v64
	v_cmp_ge_f32_e64 s[50:51], 0, v65
	v_cndmask_b32_e64 v49, v49, v54, s[54:55]
	v_fma_f32 v69, -v60, v52, v48
	v_cndmask_b32_e64 v51, v51, v57, s[50:51]
	v_cmp_lt_f32_e64 s[50:51], 0, v66
	v_cmp_ge_f32_e64 s[52:53], 0, v67
	v_cndmask_b32_e64 v50, v50, v56, s[48:49]
	v_mul_f32_e32 v53, 0x37800000, v49
	v_cndmask_b32_e64 v52, v52, v59, s[52:53]
	v_cmp_lt_f32_e64 s[52:53], 0, v69
	v_cndmask_b32_e64 v51, v51, v58, s[50:51]
	v_mul_f32_e32 v54, 0x37800000, v50
	v_cndmask_b32_e64 v49, v49, v53, s[46:47]
	v_cmp_class_f32_e64 s[46:47], v2, v202
	v_cndmask_b32_e64 v52, v52, v60, s[52:53]
	v_mul_f32_e32 v55, 0x37800000, v51
	v_cndmask_b32_e32 v50, v50, v54, vcc
	v_cmp_class_f32_e32 vcc, v46, v202
	v_cndmask_b32_e64 v2, v49, v2, s[46:47]
	v_mul_f32_e32 v56, 0x37800000, v52
	v_cndmask_b32_e64 v51, v51, v55, s[42:43]
	v_cmp_class_f32_e64 s[42:43], v47, v202
	v_cndmask_b32_e32 v46, v50, v46, vcc
	v_div_scale_f32 v49, s[6:7], v2, v2, 1.0
	v_cndmask_b32_e64 v52, v52, v56, s[44:45]
	v_cmp_class_f32_e64 s[44:45], v48, v202
	v_cndmask_b32_e64 v47, v51, v47, s[42:43]
	v_div_scale_f32 v51, s[6:7], v46, v46, 1.0
	v_rcp_f32_e32 v57, v49
	v_cndmask_b32_e64 v48, v52, v48, s[44:45]
	v_div_scale_f32 v53, s[6:7], v47, v47, 1.0
	v_rcp_f32_e32 v58, v51
	v_div_scale_f32 v55, s[6:7], v48, v48, 1.0
	v_rcp_f32_e32 v59, v53
	v_rcp_f32_e32 v60, v55
	v_fma_f32 v61, -v49, v57, 1.0
	v_div_scale_f32 v50, vcc, 1.0, v2, 1.0
	v_fma_f32 v62, -v51, v58, 1.0
	v_fmac_f32_e32 v57, v61, v57
	v_div_scale_f32 v52, s[42:43], 1.0, v46, 1.0
	v_fma_f32 v63, -v53, v59, 1.0
	v_fmac_f32_e32 v58, v62, v58
	v_mul_f32_e32 v61, v50, v57
	v_div_scale_f32 v54, s[44:45], 1.0, v47, 1.0
	v_fma_f32 v64, -v55, v60, 1.0
	v_fmac_f32_e32 v59, v63, v59
	v_mul_f32_e32 v62, v52, v58
	v_fma_f32 v65, -v49, v61, v50
	v_div_scale_f32 v56, s[46:47], 1.0, v48, 1.0
	v_fmac_f32_e32 v60, v64, v60
	v_mul_f32_e32 v63, v54, v59
	v_fma_f32 v66, -v51, v62, v52
	v_fmac_f32_e32 v61, v65, v57
	v_mul_f32_e32 v64, v56, v60
	v_fma_f32 v67, -v53, v63, v54
	v_fmac_f32_e32 v62, v66, v58
	v_fma_f32 v49, -v49, v61, v50
	v_fma_f32 v69, -v55, v64, v56
	v_fmac_f32_e32 v63, v67, v59
	v_fma_f32 v50, -v51, v62, v52
	v_div_fmas_f32 v49, v49, v57, v61
	s_mov_b64 vcc, s[42:43]
	v_fmac_f32_e32 v64, v69, v60
	v_fma_f32 v51, -v53, v63, v54
	v_div_fixup_f32 v2, v49, v2, 1.0
	v_div_fmas_f32 v49, v50, v58, v62
	s_mov_b64 vcc, s[44:45]
	v_fma_f32 v52, -v55, v64, v56
	v_pk_mul_f32 v[32:33], v[32:33], v[2:3] op_sel_hi:[1,0]
	v_pk_mul_f32 v[34:35], v[34:35], v[2:3] op_sel_hi:[1,0]
	v_pk_mul_f32 v[28:29], v[28:29], v[2:3] op_sel_hi:[1,0]
	v_pk_mul_f32 v[30:31], v[30:31], v[2:3] op_sel_hi:[1,0]
	v_div_fixup_f32 v2, v49, v46, 1.0
	v_div_fmas_f32 v46, v51, v59, v63
	s_mov_b64 vcc, s[46:47]
	v_cvt_pk_bf16_f32 v28, v28, v29
	v_cvt_pk_bf16_f32 v29, v30, v31
	v_pk_mul_f32 v[24:25], v[24:25], v[2:3] op_sel_hi:[1,0]
	v_pk_mul_f32 v[26:27], v[26:27], v[2:3] op_sel_hi:[1,0]
	v_pk_mul_f32 v[20:21], v[20:21], v[2:3] op_sel_hi:[1,0]
	v_pk_mul_f32 v[22:23], v[22:23], v[2:3] op_sel_hi:[1,0]
	v_div_fixup_f32 v2, v46, v47, 1.0
	v_div_fmas_f32 v30, v52, v60, v64
	v_pk_mul_f32 v[16:17], v[16:17], v[2:3] op_sel_hi:[1,0]
	v_pk_mul_f32 v[18:19], v[18:19], v[2:3] op_sel_hi:[1,0]
	v_pk_mul_f32 v[12:13], v[12:13], v[2:3] op_sel_hi:[1,0]
	v_pk_mul_f32 v[14:15], v[14:15], v[2:3] op_sel_hi:[1,0]
	v_div_fixup_f32 v2, v30, v48, 1.0
	v_pk_mul_f32 v[8:9], v[8:9], v[2:3] op_sel_hi:[1,0]
	v_pk_mul_f32 v[10:11], v[10:11], v[2:3] op_sel_hi:[1,0]
	v_cvt_pk_bf16_f32 v32, v32, v33
	v_cvt_pk_bf16_f32 v33, v34, v35
	v_cvt_pk_bf16_f32 v24, v24, v25
	v_cvt_pk_bf16_f32 v25, v26, v27
	v_cvt_pk_bf16_f32 v16, v16, v17
	v_cvt_pk_bf16_f32 v17, v18, v19
	v_pk_mul_f32 v[4:5], v[4:5], v[2:3] op_sel_hi:[1,0]
	v_pk_mul_f32 v[6:7], v[6:7], v[2:3] op_sel_hi:[1,0]
	v_cvt_pk_bf16_f32 v8, v8, v9
	v_cvt_pk_bf16_f32 v9, v10, v11
	global_store_dwordx2 v[36:37], v[32:33], off
	global_store_dwordx2 v[36:37], v[28:29], off offset:512
	v_cvt_pk_bf16_f32 v20, v20, v21
	v_cvt_pk_bf16_f32 v21, v22, v23
	global_store_dwordx2 v[36:37], v[24:25], off offset:1024
	global_store_dwordx2 v[36:37], v[20:21], off offset:1536
	v_cvt_pk_bf16_f32 v12, v12, v13
	v_cvt_pk_bf16_f32 v13, v14, v15
	global_store_dwordx2 v[36:37], v[16:17], off offset:2048
	global_store_dwordx2 v[36:37], v[12:13], off offset:2560
	v_cvt_pk_bf16_f32 v4, v4, v5
	v_cvt_pk_bf16_f32 v5, v6, v7
	global_store_dwordx2 v[36:37], v[8:9], off offset:3072
	global_store_dwordx2 v[36:37], v[4:5], off offset:3584
	v_lshl_add_u64 v[36:37], v[36:37], 0, s[16:17]
	s_cbranch_scc0 .LBB0_139
